# kt-MFMA version + 1024-cycle stagger of waves 4-7 at the start of the gdn_intra conv step
# baseline (speedup 1.0000x reference)
; #define LAS __attribute__((address_space(3)))
; DI void unpack8(u32x4 w, float* f) { f[0] = bflo(w.x); f[1] = bfhi(w.x); f[2] = bflo(w.y); f[3] = bfhi(w.y); f[4] = bflo(w.z); f[5] = bfhi(w.z); f[6] = bflo(w.w); f[7] = bfhi(w.w); }
; DI void lds_barrier() { asm volatile("s_waitcnt lgkmcnt(0)" ::: "memory"); __builtin_amdgcn_s_barrier(); asm volatile("" ::: "memory"); }
; DI void gdn_intra(LAS unsigned char* lds, PP p, int l, int first, int stride) {
;     ...
;     lds_barrier();
; #pragma unroll
;     for (int mat = 0; mat < 3; ++mat) {
; #pragma unroll
;         for (int it = 0; it < 2; ++it) {
;             const int id = tid + NTHR * it, j = id >> 4, o = id & 15;
;             float a[8];
; #pragma unroll
;             for (int i = 0; i < 8; ++i) a[i] = 0.f;
; #pragma unroll
;             for (int kk = 0; kk < 4; ++kk) { const bool ok = tok0 + j - 3 + kk >= 0;
;                 float x[8]; unpack8(R[(mat * 2 + it) * 4 + kk], x);
;                 const f32x4 w0 = *(const LAS f32x4*)(CW + kk * 384 + mat * 128 + o * 8), w1 = *(const LAS f32x4*)(CW + kk * 384 + mat * 128 + o * 8 + 4);
;                 for (int i = 0; i < 4; ++i) { a[i] += ok ? w0[i] * x[i] : 0.f; a[4 + i] += ok ? w1[i] * x[4 + i] : 0.f; } }
.LBB0_430:
	s_or_b64 exec, exec, s[2:3]
	v_and_b32_e32 v28, 15, v138
	v_lshlrev_b32_e32 v20, 5, v28
	s_waitcnt lgkmcnt(0)
	s_barrier
	v_readfirstlane_b32 s2, v201
	s_cmp_lt_u32 s2, 256
	s_cbranch_scc1 .Lstag_skip
	s_sleep 16
.Lstag_skip:
	v_add_u32_e32 v26, v0, v20
	ds_read_b128 v[12:15], v26
	ds_read_b128 v[16:19], v26 offset:16
	s_lshl_b32 s2, s54, 6
	s_and_b32 s20, s2, 0x3fc0
	v_ashrrev_i32_e32 v24, 4, v138
	v_add_u32_e32 v21, s20, v24
	v_lshlrev_b32_e32 v0, 16, v38
	v_lshlrev_b32_e32 v4, 16, v36
	v_and_b32_e32 v2, 0xffff0000, v38
	s_waitcnt lgkmcnt(1)
	v_fma_f32 v4, v12, v4, 0
	s_waitcnt lgkmcnt(0)
	v_mul_f32_e32 v5, v16, v0
	v_cmp_lt_i32_e64 s[40:41], 2, v21
	v_and_b32_e32 v1, 0xffff0000, v36
	v_fma_f32 v1, v13, v1, 0
	v_cndmask_b32_e64 v0, 0, v4, s[40:41]
	v_cndmask_b32_e64 v4, 0, v5, s[40:41]
	v_mul_f32_e32 v5, v17, v2
	v_cndmask_b32_e64 v5, 0, v5, s[40:41]
	v_cmp_gt_i32_e64 s[30:31], 3, v21
	v_add_f32_e32 v4, 0, v4
	v_cndmask_b32_e64 v1, 0, v1, s[40:41]
	v_mov_b32_e32 v2, v3
	v_mov_b32_e32 v6, v3
	v_mov_b32_e32 v7, v3
	v_add_f32_e32 v5, 0, v5
	s_and_saveexec_b64 s[2:3], s[30:31]
	s_xor_b64 s[2:3], exec, s[2:3]
	s_or_saveexec_b64 s[2:3], s[2:3]
	v_mov_b32_e32 v8, 0
	s_xor_b64 exec, exec, s[2:3]
	v_lshlrev_b32_e32 v8, 16, v39
	v_lshlrev_b32_e32 v2, 16, v37
	v_fma_f32 v2, v14, v2, 0
	v_mul_f32_e32 v8, v18, v8
	s_or_b64 exec, exec, s[2:3]
	v_add_f32_e32 v12, v6, v8
	v_mov_b64_e32 v[10:11], v[6:7]
	v_mov_b64_e32 v[8:9], v[4:5]
	v_mov_b64_e32 v[6:7], v[2:3]
	v_mov_b64_e32 v[4:5], v[0:1]
	v_mov_b32_e32 v10, v12
	s_and_saveexec_b64 s[2:3], s[30:31]
	s_xor_b64 s[2:3], exec, s[2:3]
	v_add_f32_e32 v7, 0, v3
	s_or_saveexec_b64 s[2:3], s[2:3]
	v_mov_b32_e32 v0, 0
	s_xor_b64 exec, exec, s[2:3]
	v_and_b32_e32 v0, 0xffff0000, v37
	v_and_b32_e32 v1, 0xffff0000, v39
	v_mov_b32_e32 v7, v3
	v_fmac_f32_e32 v7, v15, v0
	v_mul_f32_e32 v0, v19, v1
	s_or_b64 exec, exec, s[2:3]
	ds_read_b128 v[12:15], v26 offset:1536
	ds_read_b128 v[16:19], v26 offset:1552
	v_add_f32_e32 v11, v11, v0
	v_cmp_gt_i32_e64 s[24:25], 2, v21
	s_and_saveexec_b64 s[2:3], s[24:25]
	s_xor_b64 s[2:3], exec, s[2:3]
	v_add_f32_e32 v4, 0, v4
	s_or_saveexec_b64 s[2:3], s[2:3]
	v_mov_b32_e32 v0, 0
	s_xor_b64 exec, exec, s[2:3]
	s_cbranch_execz .LBB0_440
	v_lshlrev_b32_e32 v0, 16, v42
	v_lshlrev_b32_e32 v1, 16, v40
	s_waitcnt lgkmcnt(1)
	v_fmac_f32_e32 v4, v12, v1
	s_waitcnt lgkmcnt(0)
	v_mul_f32_e32 v0, v16, v0
